# attention steady loop: the two LDS-DMA issues per step moved from the serial row-max section into QK MFMA gaps, dead M0 save/restore dropped
# baseline (speedup 1.0000x reference)
.LBB0_783:
	v_add_u32_e32 v0, s20, v230
	ds_read_b64_tr_b16 v[192:193], v0 offset:24576
	ds_read_b64_tr_b16 v[194:195], v0 offset:25088
	s_waitcnt lgkmcnt(9)
	v_mfma_f32_32x32x16_bf16 v[112:127], v[188:191], v[148:151], v[48:63]
	v_add_f32_e32 v2, v80, v81
	v_add_f32_e32 v2, v82, v2
	v_add_f32_e32 v2, v83, v2
	v_add_f32_e32 v2, v84, v2
	v_add_f32_e32 v2, v85, v2
	v_cvt_pk_bf16_f32 v156, v80, v81
	v_cvt_pk_bf16_f32 v157, v82, v83
	ds_read_b64_tr_b16 v[80:81], v0 offset:28672
	ds_read_b64_tr_b16 v[82:83], v0 offset:29184
	s_waitcnt lgkmcnt(10)
	v_mfma_f32_32x32x16_bf16 v[96:111], v[184:187], v[148:151], v[48:63]
	v_add_f32_e32 v2, v86, v2
	v_add_f32_e32 v2, v87, v2
	v_add_f32_e32 v2, v88, v2
	v_add_f32_e32 v6, v89, v2
	v_cvt_pk_bf16_f32 v158, v84, v85
	v_cvt_pk_bf16_f32 v159, v86, v87
	s_add_i32 s1, s24, s27
	s_mov_b32 m0, s1
	s_add_u32 s20, s18, 0xffe38000
	s_addc_u32 s21, s19, -1
	global_load_lds_dwordx4 v227, s[20:21]
	ds_read_b64_tr_b16 v[2:3], v0 offset:25600
	ds_read_b64_tr_b16 v[4:5], v0 offset:26112
	s_waitcnt lgkmcnt(11)
	v_mfma_f32_32x32x16_bf16 v[112:127], v[180:183], v[136:139], v[112:127]
	v_add_f32_e32 v6, v90, v6
	v_add_f32_e32 v6, v91, v6
	v_add_f32_e32 v6, v92, v6
	v_add_f32_e32 v10, v93, v6
	v_cvt_pk_bf16_f32 v152, v88, v89
	v_cvt_pk_bf16_f32 v153, v90, v91
	ds_read_b64_tr_b16 v[6:7], v0 offset:29696
	ds_read_b64_tr_b16 v[8:9], v0 offset:30208
	s_waitcnt lgkmcnt(12)
	v_mfma_f32_32x32x16_bf16 v[96:111], v[176:179], v[136:139], v[96:111]
	v_add_f32_e32 v10, v94, v10
	v_add_f32_e32 v10, v95, v10
	v_add_f32_e32 v10, v64, v10
	v_add_f32_e32 v14, v65, v10
	v_cvt_pk_bf16_f32 v154, v92, v93
	v_cvt_pk_bf16_f32 v155, v94, v95
	s_add_i32 s1, s2, s30
	s_mov_b32 m0, s1
	s_add_u32 s20, s16, 0xffe38000
	s_addc_u32 s21, s17, -1
	global_load_lds_dwordx4 v228, s[20:21]
	ds_read_b64_tr_b16 v[10:11], v0 offset:26624
	ds_read_b64_tr_b16 v[12:13], v0 offset:27136
	s_waitcnt lgkmcnt(13)
	v_mfma_f32_32x32x16_bf16 v[112:127], v[172:175], v[132:135], v[112:127]
	v_add_f32_e32 v14, v66, v14
	v_add_f32_e32 v14, v67, v14
	v_add_f32_e32 v14, v68, v14
	v_add_f32_e32 v14, v69, v14
	v_cvt_pk_bf16_f32 v144, v64, v65
	v_cvt_pk_bf16_f32 v145, v66, v67
	ds_read_b64_tr_b16 v[64:65], v0 offset:30720
	ds_read_b64_tr_b16 v[66:67], v0 offset:31232
	s_waitcnt lgkmcnt(14)
	v_mfma_f32_32x32x16_bf16 v[96:111], v[168:171], v[132:135], v[96:111]
	v_add_f32_e32 v14, v70, v14
	v_add_f32_e32 v14, v71, v14
	v_add_f32_e32 v14, v72, v14
	v_add_f32_e32 v14, v73, v14
	v_cvt_pk_bf16_f32 v146, v68, v69
	v_cvt_pk_bf16_f32 v147, v70, v71
	ds_read_b64_tr_b16 v[68:69], v0 offset:27648
	ds_read_b64_tr_b16 v[70:71], v0 offset:28160
	s_waitcnt lgkmcnt(14)
	v_mfma_f32_32x32x16_bf16 v[112:127], v[164:167], v[128:131], v[112:127]
	v_add_f32_e32 v14, v74, v14
	v_add_f32_e32 v14, v75, v14
	v_add_f32_e32 v14, v76, v14
	v_add_f32_e32 v14, v77, v14
	v_cvt_pk_bf16_f32 v140, v72, v73
	v_cvt_pk_bf16_f32 v141, v74, v75
	ds_read_b64_tr_b16 v[72:73], v0 offset:31744
	ds_read_b64_tr_b16 v[74:75], v0 offset:32256
	v_mfma_f32_32x32x16_bf16 v[96:111], v[160:163], v[128:131], v[96:111]
	v_add_f32_e32 v0, v78, v14
	v_add_f32_e32 v0, v79, v0
	v_add_f32_e32 v0, 0, v0
	v_cvt_pk_bf16_f32 v142, v76, v77
	v_cvt_pk_bf16_f32 v143, v78, v79
	v_max_f32_e32 v14, v112, v113
	s_nop 5
	v_max3_f32 v15, v114, v115, v97
	v_max3_f32 v14, v14, v96, v98
	v_max3_f32 v14, v14, v99, v116
	v_max3_f32 v15, v15, v118, v119
	v_max3_f32 v14, v14, v117, v100
	v_max3_f32 v15, v15, v102, v103
	v_max3_f32 v14, v14, v101, v120
	v_max3_f32 v15, v15, v122, v123
	v_max3_f32 v14, v14, v121, v104
	v_max3_f32 v15, v15, v106, v107
	v_max3_f32 v14, v14, v105, v124
	v_max3_f32 v15, v15, v126, v127
	v_max3_f32 v76, v14, v125, v108
	v_max3_f32 v15, v15, v110, v111
	v_add_f32_e32 v14, v232, v0
	v_max3_f32 v0, v76, v109, v15
	v_mov_b32_e32 v15, v0
	s_nop 1
	v_permlane32_swap_b32_e32 v0, v15
	v_max_f32_e32 v0, v0, v15
	s_mov_b32 s1, 0x41000000
	v_cmp_lt_f32_e32 vcc, s1, v0
	s_cmp_lg_u64 vcc, 0
	s_cselect_b64 s[20:21], -1, 0
	s_cbranch_vccnz .LBB0_791

.LBB0_786:
	s_add_i32 s1, s2, 0x2000
	s_cmpk_lg_i32 s2, 0x4000
	s_cselect_b32 s34, s1, 0
	v_add_u32_e32 v15, s24, v230
	ds_read_b64_tr_b16 v[160:161], v15 offset:24576
	ds_read_b64_tr_b16 v[162:163], v15 offset:25088
	s_waitcnt lgkmcnt(9)
	v_mfma_f32_32x32x16_bf16 v[80:95], v[76:79], v[148:151], v[48:63]
	v_add_f32_e32 v2, v112, v113
	v_add_f32_e32 v2, v114, v2
	v_add_f32_e32 v2, v115, v2
	v_add_f32_e32 v2, v116, v2
	v_add_f32_e32 v2, v117, v2
	v_cvt_pk_bf16_f32 v156, v112, v113
	v_cvt_pk_bf16_f32 v157, v114, v115
	ds_read_b64_tr_b16 v[112:113], v15 offset:28672
	ds_read_b64_tr_b16 v[114:115], v15 offset:29184
	s_waitcnt lgkmcnt(10)
	v_mfma_f32_32x32x16_bf16 v[64:79], v[184:187], v[148:151], v[48:63]
	v_add_f32_e32 v2, v118, v2
	v_add_f32_e32 v2, v119, v2
	v_add_f32_e32 v2, v120, v2
	v_add_f32_e32 v6, v121, v2
	v_cvt_pk_bf16_f32 v158, v116, v117
	v_cvt_pk_bf16_f32 v159, v118, v119
	s_add_i32 s1, s2, s27
	s_mov_b32 m0, s1
	s_nop 0
	global_load_lds_dwordx4 v227, s[18:19]
	ds_read_b64_tr_b16 v[2:3], v15 offset:25600
	ds_read_b64_tr_b16 v[4:5], v15 offset:26112
	s_waitcnt lgkmcnt(11)
	v_mfma_f32_32x32x16_bf16 v[80:95], v[188:191], v[136:139], v[80:95]
	v_add_f32_e32 v6, v122, v6
	v_add_f32_e32 v6, v123, v6
	v_add_f32_e32 v6, v124, v6
	v_add_f32_e32 v10, v125, v6
	v_cvt_pk_bf16_f32 v152, v120, v121
	v_cvt_pk_bf16_f32 v153, v122, v123
	ds_read_b64_tr_b16 v[6:7], v15 offset:29696
	ds_read_b64_tr_b16 v[8:9], v15 offset:30208
	s_waitcnt lgkmcnt(12)
	v_mfma_f32_32x32x16_bf16 v[64:79], v[180:183], v[136:139], v[64:79]
	v_add_f32_e32 v10, v126, v10
	v_add_f32_e32 v10, v127, v10
	v_add_f32_e32 v10, v96, v10
	v_add_f32_e32 v116, v97, v10
	v_cvt_pk_bf16_f32 v154, v124, v125
	v_cvt_pk_bf16_f32 v155, v126, v127
	s_add_i32 s1, s34, s30
	s_mov_b32 m0, s1
	s_nop 0
	global_load_lds_dwordx4 v228, s[16:17]
	ds_read_b64_tr_b16 v[10:11], v15 offset:26624
	ds_read_b64_tr_b16 v[12:13], v15 offset:27136
	s_waitcnt lgkmcnt(13)
	v_mfma_f32_32x32x16_bf16 v[80:95], v[176:179], v[132:135], v[80:95]
	v_add_f32_e32 v116, v98, v116
	v_add_f32_e32 v116, v99, v116
	v_add_f32_e32 v116, v100, v116
	v_add_f32_e32 v116, v101, v116
	v_cvt_pk_bf16_f32 v144, v96, v97
	v_cvt_pk_bf16_f32 v145, v98, v99
	ds_read_b64_tr_b16 v[96:97], v15 offset:30720
	ds_read_b64_tr_b16 v[98:99], v15 offset:31232
	s_waitcnt lgkmcnt(14)
	v_mfma_f32_32x32x16_bf16 v[64:79], v[172:175], v[132:135], v[64:79]
	v_add_f32_e32 v116, v102, v116
	v_add_f32_e32 v116, v103, v116
	v_add_f32_e32 v116, v104, v116
	v_add_f32_e32 v116, v105, v116
	v_cvt_pk_bf16_f32 v146, v100, v101
	v_cvt_pk_bf16_f32 v147, v102, v103
	ds_read_b64_tr_b16 v[100:101], v15 offset:27648
	ds_read_b64_tr_b16 v[102:103], v15 offset:28160
	s_waitcnt lgkmcnt(14)
	v_mfma_f32_32x32x16_bf16 v[80:95], v[168:171], v[128:131], v[80:95]
	v_add_f32_e32 v116, v106, v116
	v_add_f32_e32 v116, v107, v116
	v_add_f32_e32 v116, v108, v116
	v_add_f32_e32 v116, v109, v116
	v_cvt_pk_bf16_f32 v140, v104, v105
	v_cvt_pk_bf16_f32 v141, v106, v107
	ds_read_b64_tr_b16 v[104:105], v15 offset:31744
	ds_read_b64_tr_b16 v[106:107], v15 offset:32256
	v_mfma_f32_32x32x16_bf16 v[64:79], v[164:167], v[128:131], v[64:79]
	v_add_f32_e32 v15, v110, v116
	v_add_f32_e32 v15, v111, v15
	v_add_f32_e32 v15, 0, v15
	v_cvt_pk_bf16_f32 v142, v108, v109
	v_cvt_pk_bf16_f32 v143, v110, v111
	v_max_f32_e32 v108, v80, v81
	s_nop 5
	v_max3_f32 v109, v82, v83, v65
	v_max3_f32 v108, v108, v64, v66
	v_max3_f32 v108, v108, v67, v84
	v_max3_f32 v109, v109, v86, v87
	v_max3_f32 v108, v108, v85, v68
	v_max3_f32 v109, v109, v70, v71
	v_max3_f32 v108, v108, v69, v88
	v_max3_f32 v109, v109, v90, v91
	v_max3_f32 v108, v108, v89, v72
	v_max3_f32 v109, v109, v74, v75
	v_max3_f32 v108, v108, v73, v92
	v_max3_f32 v109, v109, v94, v95
	v_max3_f32 v108, v108, v93, v76
	v_max3_f32 v109, v109, v78, v79
	v_add_f32_e32 v232, v14, v15
	v_max3_f32 v14, v108, v77, v109
	v_mov_b32_e32 v15, v14
	s_nop 1
	v_permlane32_swap_b32_e32 v14, v15
	v_max_f32_e32 v14, v14, v15
	s_mov_b32 s1, 0x41000000
	v_cmp_lt_f32_e32 vcc, s1, v14
	s_cmp_lg_u64 vcc, 0
	s_cselect_b64 s[20:21], -1, 0
	s_cbranch_vccnz .LBB0_794

.LBB0_2404:
	v_add_u32_e32 v0, s20, v231
	ds_read_b64_tr_b16 v[192:193], v0 offset:24576
	ds_read_b64_tr_b16 v[194:195], v0 offset:25088
	s_waitcnt lgkmcnt(9)
	v_mfma_f32_32x32x16_bf16 v[112:127], v[188:191], v[148:151], v[48:63]
	v_add_f32_e32 v2, v80, v81
	v_add_f32_e32 v2, v82, v2
	v_add_f32_e32 v2, v83, v2
	v_add_f32_e32 v2, v84, v2
	v_add_f32_e32 v2, v85, v2
	v_cvt_pk_bf16_f32 v156, v80, v81
	v_cvt_pk_bf16_f32 v157, v82, v83
	ds_read_b64_tr_b16 v[80:81], v0 offset:28672
	ds_read_b64_tr_b16 v[82:83], v0 offset:29184
	s_waitcnt lgkmcnt(10)
	v_mfma_f32_32x32x16_bf16 v[96:111], v[184:187], v[148:151], v[48:63]
	v_add_f32_e32 v2, v86, v2
	v_add_f32_e32 v2, v87, v2
	v_add_f32_e32 v2, v88, v2
	v_add_f32_e32 v6, v89, v2
	v_cvt_pk_bf16_f32 v158, v84, v85
	v_cvt_pk_bf16_f32 v159, v86, v87
	s_add_i32 s0, s24, s27
	s_mov_b32 m0, s0
	s_add_u32 s20, s18, 0xffe38000
	s_addc_u32 s21, s19, -1
	global_load_lds_dwordx4 v228, s[20:21]
	ds_read_b64_tr_b16 v[2:3], v0 offset:25600
	ds_read_b64_tr_b16 v[4:5], v0 offset:26112
	s_waitcnt lgkmcnt(11)
	v_mfma_f32_32x32x16_bf16 v[112:127], v[180:183], v[136:139], v[112:127]
	v_add_f32_e32 v6, v90, v6
	v_add_f32_e32 v6, v91, v6
	v_add_f32_e32 v6, v92, v6
	v_add_f32_e32 v10, v93, v6
	v_cvt_pk_bf16_f32 v152, v88, v89
	v_cvt_pk_bf16_f32 v153, v90, v91
	ds_read_b64_tr_b16 v[6:7], v0 offset:29696
	ds_read_b64_tr_b16 v[8:9], v0 offset:30208
	s_waitcnt lgkmcnt(12)
	v_mfma_f32_32x32x16_bf16 v[96:111], v[176:179], v[136:139], v[96:111]
	v_add_f32_e32 v10, v94, v10
	v_add_f32_e32 v10, v95, v10
	v_add_f32_e32 v10, v64, v10
	v_add_f32_e32 v14, v65, v10
	v_cvt_pk_bf16_f32 v154, v92, v93
	v_cvt_pk_bf16_f32 v155, v94, v95
	s_add_i32 s0, s2, s30
	s_mov_b32 m0, s0
	s_add_u32 s20, s16, 0xffe38000
	s_addc_u32 s21, s17, -1
	global_load_lds_dwordx4 v229, s[20:21]
	ds_read_b64_tr_b16 v[10:11], v0 offset:26624
	ds_read_b64_tr_b16 v[12:13], v0 offset:27136
	s_waitcnt lgkmcnt(13)
	v_mfma_f32_32x32x16_bf16 v[112:127], v[172:175], v[132:135], v[112:127]
	v_add_f32_e32 v14, v66, v14
	v_add_f32_e32 v14, v67, v14
	v_add_f32_e32 v14, v68, v14
	v_add_f32_e32 v14, v69, v14
	v_cvt_pk_bf16_f32 v144, v64, v65
	v_cvt_pk_bf16_f32 v145, v66, v67
	ds_read_b64_tr_b16 v[64:65], v0 offset:30720
	ds_read_b64_tr_b16 v[66:67], v0 offset:31232
	s_waitcnt lgkmcnt(14)
	v_mfma_f32_32x32x16_bf16 v[96:111], v[168:171], v[132:135], v[96:111]
	v_add_f32_e32 v14, v70, v14
	v_add_f32_e32 v14, v71, v14
	v_add_f32_e32 v14, v72, v14
	v_add_f32_e32 v14, v73, v14
	v_cvt_pk_bf16_f32 v146, v68, v69
	v_cvt_pk_bf16_f32 v147, v70, v71
	ds_read_b64_tr_b16 v[68:69], v0 offset:27648
	ds_read_b64_tr_b16 v[70:71], v0 offset:28160
	s_waitcnt lgkmcnt(14)
	v_mfma_f32_32x32x16_bf16 v[112:127], v[164:167], v[128:131], v[112:127]
	v_add_f32_e32 v14, v74, v14
	v_add_f32_e32 v14, v75, v14
	v_add_f32_e32 v14, v76, v14
	v_add_f32_e32 v14, v77, v14
	v_cvt_pk_bf16_f32 v140, v72, v73
	v_cvt_pk_bf16_f32 v141, v74, v75
	ds_read_b64_tr_b16 v[72:73], v0 offset:31744
	ds_read_b64_tr_b16 v[74:75], v0 offset:32256
	v_mfma_f32_32x32x16_bf16 v[96:111], v[160:163], v[128:131], v[96:111]
	v_add_f32_e32 v0, v78, v14
	v_add_f32_e32 v0, v79, v0
	v_add_f32_e32 v0, 0, v0
	v_cvt_pk_bf16_f32 v142, v76, v77
	v_cvt_pk_bf16_f32 v143, v78, v79
	v_max_f32_e32 v14, v112, v113
	s_nop 5
	v_max3_f32 v15, v114, v115, v97
	v_max3_f32 v14, v14, v96, v98
	v_max3_f32 v14, v14, v99, v116
	v_max3_f32 v15, v15, v118, v119
	v_max3_f32 v14, v14, v117, v100
	v_max3_f32 v15, v15, v102, v103
	v_max3_f32 v14, v14, v101, v120
	v_max3_f32 v15, v15, v122, v123
	v_max3_f32 v14, v14, v121, v104
	v_max3_f32 v15, v15, v106, v107
	v_max3_f32 v14, v14, v105, v124
	v_max3_f32 v15, v15, v126, v127
	v_max3_f32 v76, v14, v125, v108
	v_max3_f32 v15, v15, v110, v111
	v_add_f32_e32 v14, v233, v0
	v_max3_f32 v0, v76, v109, v15
	v_mov_b32_e32 v15, v0
	s_nop 1
	v_permlane32_swap_b32_e32 v0, v15
	v_max_f32_e32 v0, v0, v15
	v_cmp_lt_f32_e32 vcc, s49, v0
	s_cmp_lg_u64 vcc, 0
	s_cselect_b64 s[20:21], -1, 0
	s_cbranch_vccnz .LBB0_2412

.LBB0_2407:
	s_add_i32 s0, s2, 0x2000
	s_cmpk_lg_i32 s2, 0x4000
	s_cselect_b32 s34, s0, 0
	v_add_u32_e32 v15, s24, v231
	ds_read_b64_tr_b16 v[160:161], v15 offset:24576
	ds_read_b64_tr_b16 v[162:163], v15 offset:25088
	s_waitcnt lgkmcnt(9)
	v_mfma_f32_32x32x16_bf16 v[80:95], v[76:79], v[148:151], v[48:63]
	v_add_f32_e32 v2, v112, v113
	v_add_f32_e32 v2, v114, v2
	v_add_f32_e32 v2, v115, v2
	v_add_f32_e32 v2, v116, v2
	v_add_f32_e32 v2, v117, v2
	v_cvt_pk_bf16_f32 v156, v112, v113
	v_cvt_pk_bf16_f32 v157, v114, v115
	ds_read_b64_tr_b16 v[112:113], v15 offset:28672
	ds_read_b64_tr_b16 v[114:115], v15 offset:29184
	s_waitcnt lgkmcnt(10)
	v_mfma_f32_32x32x16_bf16 v[64:79], v[184:187], v[148:151], v[48:63]
	v_add_f32_e32 v2, v118, v2
	v_add_f32_e32 v2, v119, v2
	v_add_f32_e32 v2, v120, v2
	v_add_f32_e32 v6, v121, v2
	v_cvt_pk_bf16_f32 v158, v116, v117
	v_cvt_pk_bf16_f32 v159, v118, v119
	s_add_i32 s0, s2, s27
	s_mov_b32 m0, s0
	s_nop 0
	global_load_lds_dwordx4 v228, s[18:19]
	ds_read_b64_tr_b16 v[2:3], v15 offset:25600
	ds_read_b64_tr_b16 v[4:5], v15 offset:26112
	s_waitcnt lgkmcnt(11)
	v_mfma_f32_32x32x16_bf16 v[80:95], v[188:191], v[136:139], v[80:95]
	v_add_f32_e32 v6, v122, v6
	v_add_f32_e32 v6, v123, v6
	v_add_f32_e32 v6, v124, v6
	v_add_f32_e32 v10, v125, v6
	v_cvt_pk_bf16_f32 v152, v120, v121
	v_cvt_pk_bf16_f32 v153, v122, v123
	ds_read_b64_tr_b16 v[6:7], v15 offset:29696
	ds_read_b64_tr_b16 v[8:9], v15 offset:30208
	s_waitcnt lgkmcnt(12)
	v_mfma_f32_32x32x16_bf16 v[64:79], v[180:183], v[136:139], v[64:79]
	v_add_f32_e32 v10, v126, v10
	v_add_f32_e32 v10, v127, v10
	v_add_f32_e32 v10, v96, v10
	v_add_f32_e32 v116, v97, v10
	v_cvt_pk_bf16_f32 v154, v124, v125
	v_cvt_pk_bf16_f32 v155, v126, v127
	s_add_i32 s0, s34, s30
	s_mov_b32 m0, s0
	s_nop 0
	global_load_lds_dwordx4 v229, s[16:17]
	ds_read_b64_tr_b16 v[10:11], v15 offset:26624
	ds_read_b64_tr_b16 v[12:13], v15 offset:27136
	s_waitcnt lgkmcnt(13)
	v_mfma_f32_32x32x16_bf16 v[80:95], v[176:179], v[132:135], v[80:95]
	v_add_f32_e32 v116, v98, v116
	v_add_f32_e32 v116, v99, v116
	v_add_f32_e32 v116, v100, v116
	v_add_f32_e32 v116, v101, v116
	v_cvt_pk_bf16_f32 v144, v96, v97
	v_cvt_pk_bf16_f32 v145, v98, v99
	ds_read_b64_tr_b16 v[96:97], v15 offset:30720
	ds_read_b64_tr_b16 v[98:99], v15 offset:31232
	s_waitcnt lgkmcnt(14)
	v_mfma_f32_32x32x16_bf16 v[64:79], v[172:175], v[132:135], v[64:79]
	v_add_f32_e32 v116, v102, v116
	v_add_f32_e32 v116, v103, v116
	v_add_f32_e32 v116, v104, v116
	v_add_f32_e32 v116, v105, v116
	v_cvt_pk_bf16_f32 v146, v100, v101
	v_cvt_pk_bf16_f32 v147, v102, v103
	ds_read_b64_tr_b16 v[100:101], v15 offset:27648
	ds_read_b64_tr_b16 v[102:103], v15 offset:28160
	s_waitcnt lgkmcnt(14)
	v_mfma_f32_32x32x16_bf16 v[80:95], v[168:171], v[128:131], v[80:95]
	v_add_f32_e32 v116, v106, v116
	v_add_f32_e32 v116, v107, v116
	v_add_f32_e32 v116, v108, v116
	v_add_f32_e32 v116, v109, v116
	v_cvt_pk_bf16_f32 v140, v104, v105
	v_cvt_pk_bf16_f32 v141, v106, v107
	ds_read_b64_tr_b16 v[104:105], v15 offset:31744
	ds_read_b64_tr_b16 v[106:107], v15 offset:32256
	v_mfma_f32_32x32x16_bf16 v[64:79], v[164:167], v[128:131], v[64:79]
	v_add_f32_e32 v15, v110, v116
	v_add_f32_e32 v15, v111, v15
	v_add_f32_e32 v15, 0, v15
	v_cvt_pk_bf16_f32 v142, v108, v109
	v_cvt_pk_bf16_f32 v143, v110, v111
	v_max_f32_e32 v108, v80, v81
	s_nop 5
	v_max3_f32 v109, v82, v83, v65
	v_max3_f32 v108, v108, v64, v66
	v_max3_f32 v108, v108, v67, v84
	v_max3_f32 v109, v109, v86, v87
	v_max3_f32 v108, v108, v85, v68
	v_max3_f32 v109, v109, v70, v71
	v_max3_f32 v108, v108, v69, v88
	v_max3_f32 v109, v109, v90, v91
	v_max3_f32 v108, v108, v89, v72
	v_max3_f32 v109, v109, v74, v75
	v_max3_f32 v108, v108, v73, v92
	v_max3_f32 v109, v109, v94, v95
	v_max3_f32 v108, v108, v93, v76
	v_max3_f32 v109, v109, v78, v79
	v_add_f32_e32 v233, v14, v15
	v_max3_f32 v14, v108, v77, v109
	v_mov_b32_e32 v15, v14
	s_nop 1
	v_permlane32_swap_b32_e32 v14, v15
	v_max_f32_e32 v14, v14, v15
	v_cmp_lt_f32_e32 vcc, s49, v14
	s_cmp_lg_u64 vcc, 0
	s_cselect_b64 s[20:21], -1, 0
	s_cbranch_vccnz .LBB0_2415
